# v13 plus half of the workgroups start the gate/up phase 12us late so the epilogue copy bursts of the two halves interleave with the other half's K-loop
# baseline (speedup 1.0000x reference)
.LBB0_1649:
	s_or_b64 exec, exec, s[6:7]
	s_add_u32 s8, s30, 0xfc00000
	s_addc_u32 s9, s31, 0
	v_mov_b32_e32 v10, v164
	s_waitcnt lgkmcnt(0)
	s_barrier
	s_cmpk_gt_i32 s69, 0x5d7
	v_readfirstlane_b32 s7, v10
	s_cbranch_scc1 .LBB0_1665
	v_writelane_b32 v247, s78, 0
	v_writelane_b32 v247, s79, 1
	v_writelane_b32 v247, s4, 2
	v_writelane_b32 v247, s5, 3
	s_lshr_b32 s32, s69, 7
	s_lshl_b32 s32, s32, 3
	s_load_dwordx2 s[96:97], s[0:1], s32 offset:0x20
	s_load_dwordx2 s[76:77], s[0:1], 0xa0
	s_and_b32 s100, s69, 0x7f
	s_mul_i32 s100, s100, 0x300000
	s_mov_b32 s101, 0x1ee80000
	s_cmp_lt_u32 s69, 0x80
	s_cselect_b32 s101, 0x6e80000, s101
	v_and_b32_e32 v246, 63, v164
	v_lshlrev_b32_e32 v246, 4, v246
	s_waitcnt lgkmcnt(0)
	s_add_u32 s96, s96, s100
	s_addc_u32 s97, s97, 0
	s_add_u32 s96, s96, 0x3000
	s_addc_u32 s97, s97, 0
	s_and_b32 s97, s97, 0xffff
	s_mov_b32 s98, 0x300000
	s_mov_b32 s99, 0x20000
	s_add_u32 s76, s76, s101
	s_addc_u32 s77, s77, 0
	s_add_u32 s76, s76, s100
	s_addc_u32 s77, s77, 0
	s_and_b32 s77, s77, 0xffff
	s_mov_b32 s78, 0x300000
	s_mov_b32 s79, 0x20000
	s_lshr_b32 s32, s7, 6
	s_mul_i32 s101, s32, 0x0
	s_add_u32 s100, s101, 0x0
	s_mul_i32 s5, s32, 0x6000
	s_add_u32 s5, s5, 0x0
	s_mov_b32 s32, 0
	s_mov_b32 s4, 0
	v_add_u32_e32 v238, 0x1000, v246
	v_add_u32_e32 v239, 0x2000, v246
	s_mov_b32 s100, 0x70000000
	s_mov_b32 s101, 0x70000000

	s_bitcmp1_b32 s69, 3
	s_cbranch_scc0 .Lp5_nodelay
	s_sleep 127
	s_sleep 127
	s_sleep 127
.Lp5_nodelay:
	v_lshlrev_b32_e32 v0, 4, v10
	v_add_u32_e32 v1, 0x2000, v0
	v_ashrrev_i32_e32 v2, 31, v1
	v_lshrrev_b32_e32 v2, 22, v2
	v_add_u32_e32 v2, v1, v2
	v_ashrrev_i32_e32 v8, 10, v2
	v_mul_i32_i24_e32 v2, 0x400, v8
	v_sub_u32_e32 v1, v1, v2
	v_lshrrev_b32_e32 v2, 4, v1
	v_bitop3_b32 v1, v2, v1, 32 bitop3:0x6c
	v_ashrrev_i32_e32 v2, 31, v1
	v_lshrrev_b32_e32 v2, 26, v2
	v_add_u32_e32 v2, v1, v2
	v_lshlrev_b32_e32 v3, 3, v8
	v_ashrrev_i32_e32 v9, 6, v2
	v_and_b32_e32 v3, -16, v3
	v_add_u32_e32 v3, v9, v3
	v_and_b32_e32 v4, 3, v9
	s_mov_b32 s6, 0x1fffe0
	v_lshrrev_b32_e32 v5, 2, v3
	v_lshlrev_b32_e32 v6, 1, v3
	v_and_b32_e32 v2, 0xc0, v2
	v_and_or_b32 v4, v3, s6, v4
	v_and_b32_e32 v5, 4, v5
	v_and_b32_e32 v6, 24, v6
	v_sub_u32_e32 v1, v1, v2
	v_mov_b32_e32 v2, 1
	v_or3_b32 v4, v4, v5, v6
	v_lshlrev_b32_e32 v5, 5, v8
	v_ashrrev_i16_sdwa v1, v2, sext(v1) dst_sel:DWORD dst_unused:UNUSED_PAD src0_sel:DWORD src1_sel:BYTE_0
	v_and_b32_e32 v5, 32, v5
	v_bfe_i32 v11, v1, 0, 16
	v_add_lshl_u32 v1, v5, v11, 1
	v_lshl_add_u32 v130, v4, 11, v1
	v_lshl_add_u32 v132, v3, 11, v1
	v_bfe_i32 v1, v10, 27, 1
	v_lshrrev_b32_e32 v1, 22, v1
	v_add_u32_e32 v1, v0, v1
	v_and_b32_e32 v1, 0xfffffc00, v1
	v_sub_u32_e32 v0, v0, v1
	v_lshrrev_b32_e32 v1, 4, v0
	v_ashrrev_i32_e32 v3, 31, v10
	v_bitop3_b32 v0, v1, v0, 32 bitop3:0x6c
	v_lshrrev_b32_e32 v3, 26, v3
	v_ashrrev_i32_e32 v1, 31, v0
	v_add_u32_e32 v3, v10, v3
	v_lshrrev_b32_e32 v1, 26, v1
	v_ashrrev_i32_e32 v13, 6, v3
	v_add_u32_e32 v1, v0, v1
	v_lshlrev_b32_e32 v3, 3, v13
	v_ashrrev_i32_e32 v12, 6, v1
	v_and_b32_e32 v3, -16, v3
	v_add_u32_e32 v3, v12, v3
	v_and_b32_e32 v4, 3, v12
	s_ashr_i32 s14, s69, 31
	v_and_or_b32 v4, v3, s6, v4
	s_lshr_b32 s6, s14, 29
	s_add_i32 s6, s69, s6
	s_ashr_i32 s2, s7, 6
	s_ashr_i32 s11, s6, 3
	s_and_b32 s6, s6, -8
	s_ashr_i32 s10, s7, 8
	s_lshl_b32 s3, s2, 10
	s_sub_i32 s6, s69, s6
	s_cmp_lt_i32 s6, 0
	s_movk_i32 s15, 0xbc
	s_cselect_b32 s18, s15, 0xbb
	s_mul_i32 s6, s6, s18
	s_add_i32 s6, s6, s11
	s_mul_hi_i32 s11, s6, 0x2e8ba2e9
	s_lshr_b32 s18, s11, 31
	s_ashr_i32 s11, s11, 5
	v_lshrrev_b32_e32 v5, 2, v3
	v_lshlrev_b32_e32 v6, 1, v3
	v_and_b32_e32 v1, 0xc0, v1
	s_add_i32 s11, s11, s18
	v_and_b32_e32 v5, 4, v5
	v_and_b32_e32 v6, 24, v6
	v_sub_u32_e32 v0, v0, v1
	s_lshl_b32 s22, s11, 3
	v_or3_b32 v4, v4, v5, v6
	v_lshlrev_b32_e32 v5, 5, v13
	v_ashrrev_i16_sdwa v0, v2, sext(v0) dst_sel:DWORD dst_unused:UNUSED_PAD src0_sel:DWORD src1_sel:BYTE_0
	s_sub_i32 s18, 0x44, s22
	s_mulk_i32 s11, 0xb0
	v_and_b32_e32 v5, 32, v5
	v_bfe_i32 v14, v0, 0, 16
	s_min_u32 s23, s18, 8
	s_sub_i32 s11, s6, s11
	v_add_lshl_u32 v0, v5, v14, 1
	s_sext_i32_i16 s6, s11
	v_cvt_f32_ubyte0_e32 v2, s23
	v_lshl_add_u32 v134, v4, 11, v0
	v_cvt_f32_i32_e32 v1, s6
	v_rcp_iflag_f32_e32 v4, v2
	v_lshl_add_u32 v136, v3, 11, v0
	s_ashr_i32 s6, s6, 30
	s_or_b32 s6, s6, 1
	v_mul_f32_e32 v0, v1, v4
	v_trunc_f32_e32 v0, v0
	v_fma_f32 v1, -v0, v2, v1
	v_cvt_i32_f32_e32 v0, v0
	v_cmp_ge_f32_e64 s[18:19], |v1|, v2
	s_and_b64 s[18:19], s[18:19], exec
	s_cselect_b32 s6, s6, 0
	v_readfirstlane_b32 s18, v0
	s_add_i32 s6, s18, s6
	s_mul_i32 s18, s6, s23
	s_sub_i32 s11, s11, s18
	s_sext_i32_i16 s11, s11
	s_add_i32 s56, s22, s11
	s_ashr_i32 s57, s56, 31
	s_bfe_i64 s[18:19], s[6:7], 0x100000
	s_lshl_b64 s[22:23], s[56:57], 19
	s_lshl_b64 s[18:19], s[18:19], 19
	s_add_u32 s60, s92, s18
	s_addc_u32 s61, s93, s19
	s_add_i32 s18, s3, 0
	s_add_i32 m0, s18, 0x10000
	v_mov_b32_e32 v139, 0
	global_load_lds_dwordx4 v134, s[60:61]
	s_add_i32 m0, s18, 0x12000
	s_add_u32 s24, s60, 0x40000
	global_load_lds_dwordx4 v130, s[60:61]
	s_addc_u32 s25, s61, 0
	s_add_i32 m0, s18, 0x14000
	v_mov_b32_e32 v135, v139
	global_load_lds_dwordx4 v134, s[24:25]
	s_add_i32 m0, s18, 0x16000
	s_add_u32 s58, s94, s22
	s_addc_u32 s59, s95, s23
	s_add_i32 s19, s18, 0x2000
	global_load_lds_dwordx4 v130, s[24:25]
	s_mov_b32 m0, s18
	s_add_u32 s22, s58, 0x40000
	global_load_lds_dwordx4 v136, s[58:59]
	s_mov_b32 m0, s19
	s_addc_u32 s23, s59, 0
	s_add_i32 s35, s18, 0x4000
	global_load_lds_dwordx4 v132, s[58:59]
	s_mov_b32 m0, s35
	s_add_i32 s43, s18, 0x6000
	global_load_lds_dwordx4 v136, s[22:23]
	s_mov_b32 m0, s43
	v_mov_b32_e32 v131, v139
	global_load_lds_dwordx4 v132, s[22:23]
	v_mov_b32_e32 v137, v139
	v_mov_b32_e32 v133, v139
	s_cmp_eq_u32 s10, 1
	s_mov_b32 s11, 0
	v_lshl_add_u64 v[6:7], s[60:61], 0, v[134:135]
	v_lshl_add_u64 v[4:5], s[60:61], 0, v[130:131]
	v_lshl_add_u64 v[0:1], s[58:59], 0, v[136:137]
	s_cselect_b64 s[22:23], -1, 0
	s_cmp_lg_u32 s10, 1
	v_lshl_add_u64 v[2:3], s[58:59], 0, v[132:133]
	s_cbranch_scc1 .LBB0_1652
	s_barrier
